# phase 4b full-tile epilogue software-pipelined: all 16 row groups' x/mod loads issued up front, counted vmcnt waits instead of load-wait-store per row group
# speedup vs baseline: 1.0098x; 1.0098x over previous
.LBB0_767:
	v_mov_b32_e32 v36, s71
	v_mov_b32_e32 v37, s69
	v_mov_b32_e32 v38, s70
	v_mov_b32_e32 v39, s68
	v_mov_b64_e32 v[26:27], s[34:35]
	v_add_u32_e32 v24, 0, v7
	v_add_u32_e32 v14, 0xffffc000, v24
	v_lshrrev_b32_e32 v13, 3, v14
	v_ashrrev_i32_e32 v12, 11, v24
	v_ashrrev_i32_e32 v25, 31, v24
	v_add_u32_e32 v13, 8, v13
	v_cmp_gt_i32_e32 vcc, s3, v24
	s_nop 1
	v_cndmask_b32_e32 v16, v13, v12, vcc
	v_cndmask_b32_e32 v13, 0, v25, vcc
	v_cndmask_b32_e32 v12, v14, v24, vcc
	v_cndmask_b32_e32 v15, v36, v37, vcc
	v_cndmask_b32_e32 v14, v38, v39, vcc
	v_lshlrev_b64 v[12:13], 12, v[12:13]
	v_mad_i64_i32 v[16:17], s[24:25], v16, s48, v[26:27]
	v_lshl_add_u64 v[12:13], v[14:15], 0, v[12:13]
	v_lshl_add_u64 v[14:15], v[16:17], 0, v[2:3]
	v_add_co_u32_e32 v16, vcc, s50, v14
	v_lshl_add_u64 v[12:13], v[12:13], 0, v[2:3]
	s_nop 0
	v_addc_co_u32_e32 v17, vcc, 0, v15, vcc
	global_load_dwordx4 v[40:43], v[12:13], off
	s_nop 0
	global_load_dwordx4 v[174:177], v[16:17], off
	v_add_u32_e32 v24, 0, v6
	v_add_u32_e32 v14, 0xffffc000, v24
	v_lshrrev_b32_e32 v13, 3, v14
	v_ashrrev_i32_e32 v12, 11, v24
	v_ashrrev_i32_e32 v25, 31, v24
	v_add_u32_e32 v13, 8, v13
	v_cmp_gt_i32_e32 vcc, s3, v24
	s_nop 1
	v_cndmask_b32_e32 v16, v13, v12, vcc
	v_cndmask_b32_e32 v13, 0, v25, vcc
	v_cndmask_b32_e32 v12, v14, v24, vcc
	v_cndmask_b32_e32 v15, v36, v37, vcc
	v_cndmask_b32_e32 v14, v38, v39, vcc
	v_lshlrev_b64 v[12:13], 12, v[12:13]
	v_mad_i64_i32 v[16:17], s[24:25], v16, s48, v[26:27]
	v_lshl_add_u64 v[12:13], v[14:15], 0, v[12:13]
	v_lshl_add_u64 v[14:15], v[16:17], 0, v[2:3]
	v_add_co_u32_e32 v16, vcc, s50, v14
	v_lshl_add_u64 v[12:13], v[12:13], 0, v[2:3]
	s_nop 0
	v_addc_co_u32_e32 v17, vcc, 0, v15, vcc
	global_load_dwordx4 v[44:47], v[12:13], off
	s_nop 0
	global_load_dwordx4 v[178:181], v[16:17], off
	v_add_u32_e32 v24, 0, v5
	v_add_u32_e32 v14, 0xffffc000, v24
	v_lshrrev_b32_e32 v13, 3, v14
	v_ashrrev_i32_e32 v12, 11, v24
	v_ashrrev_i32_e32 v25, 31, v24
	v_add_u32_e32 v13, 8, v13
	v_cmp_gt_i32_e32 vcc, s3, v24
	s_nop 1
	v_cndmask_b32_e32 v16, v13, v12, vcc
	v_cndmask_b32_e32 v13, 0, v25, vcc
	v_cndmask_b32_e32 v12, v14, v24, vcc
	v_cndmask_b32_e32 v15, v36, v37, vcc
	v_cndmask_b32_e32 v14, v38, v39, vcc
	v_lshlrev_b64 v[12:13], 12, v[12:13]
	v_mad_i64_i32 v[16:17], s[24:25], v16, s48, v[26:27]
	v_lshl_add_u64 v[12:13], v[14:15], 0, v[12:13]
	v_lshl_add_u64 v[14:15], v[16:17], 0, v[2:3]
	v_add_co_u32_e32 v16, vcc, s50, v14
	v_lshl_add_u64 v[12:13], v[12:13], 0, v[2:3]
	s_nop 0
	v_addc_co_u32_e32 v17, vcc, 0, v15, vcc
	global_load_dwordx4 v[48:51], v[12:13], off
	s_nop 0
	global_load_dwordx4 v[182:185], v[16:17], off
	v_add_u32_e32 v24, 0, v4
	v_add_u32_e32 v14, 0xffffc000, v24
	v_lshrrev_b32_e32 v13, 3, v14
	v_ashrrev_i32_e32 v12, 11, v24
	v_ashrrev_i32_e32 v25, 31, v24
	v_add_u32_e32 v13, 8, v13
	v_cmp_gt_i32_e32 vcc, s3, v24
	s_nop 1
	v_cndmask_b32_e32 v16, v13, v12, vcc
	v_cndmask_b32_e32 v13, 0, v25, vcc
	v_cndmask_b32_e32 v12, v14, v24, vcc
	v_cndmask_b32_e32 v15, v36, v37, vcc
	v_cndmask_b32_e32 v14, v38, v39, vcc
	v_lshlrev_b64 v[12:13], 12, v[12:13]
	v_mad_i64_i32 v[16:17], s[24:25], v16, s48, v[26:27]
	v_lshl_add_u64 v[12:13], v[14:15], 0, v[12:13]
	v_lshl_add_u64 v[14:15], v[16:17], 0, v[2:3]
	v_add_co_u32_e32 v16, vcc, s50, v14
	v_lshl_add_u64 v[12:13], v[12:13], 0, v[2:3]
	s_nop 0
	v_addc_co_u32_e32 v17, vcc, 0, v15, vcc
	global_load_dwordx4 v[52:55], v[12:13], off
	s_nop 0
	global_load_dwordx4 v[186:189], v[16:17], off
	v_add_u32_e32 v24, 32, v7
	v_add_u32_e32 v14, 0xffffc000, v24
	v_lshrrev_b32_e32 v13, 3, v14
	v_ashrrev_i32_e32 v12, 11, v24
	v_ashrrev_i32_e32 v25, 31, v24
	v_add_u32_e32 v13, 8, v13
	v_cmp_gt_i32_e32 vcc, s3, v24
	s_nop 1
	v_cndmask_b32_e32 v16, v13, v12, vcc
	v_cndmask_b32_e32 v13, 0, v25, vcc
	v_cndmask_b32_e32 v12, v14, v24, vcc
	v_cndmask_b32_e32 v15, v36, v37, vcc
	v_cndmask_b32_e32 v14, v38, v39, vcc
	v_lshlrev_b64 v[12:13], 12, v[12:13]
	v_mad_i64_i32 v[16:17], s[24:25], v16, s48, v[26:27]
	v_lshl_add_u64 v[12:13], v[14:15], 0, v[12:13]
	v_lshl_add_u64 v[14:15], v[16:17], 0, v[2:3]
	v_add_co_u32_e32 v16, vcc, s50, v14
	v_lshl_add_u64 v[12:13], v[12:13], 0, v[2:3]
	s_nop 0
	v_addc_co_u32_e32 v17, vcc, 0, v15, vcc
	global_load_dwordx4 v[56:59], v[12:13], off
	s_nop 0
	global_load_dwordx4 v[190:193], v[16:17], off
	v_add_u32_e32 v24, 32, v6
	v_add_u32_e32 v14, 0xffffc000, v24
	v_lshrrev_b32_e32 v13, 3, v14
	v_ashrrev_i32_e32 v12, 11, v24
	v_ashrrev_i32_e32 v25, 31, v24
	v_add_u32_e32 v13, 8, v13
	v_cmp_gt_i32_e32 vcc, s3, v24
	s_nop 1
	v_cndmask_b32_e32 v16, v13, v12, vcc
	v_cndmask_b32_e32 v13, 0, v25, vcc
	v_cndmask_b32_e32 v12, v14, v24, vcc
	v_cndmask_b32_e32 v15, v36, v37, vcc
	v_cndmask_b32_e32 v14, v38, v39, vcc
	v_lshlrev_b64 v[12:13], 12, v[12:13]
	v_mad_i64_i32 v[16:17], s[24:25], v16, s48, v[26:27]
	v_lshl_add_u64 v[12:13], v[14:15], 0, v[12:13]
	v_lshl_add_u64 v[14:15], v[16:17], 0, v[2:3]
	v_add_co_u32_e32 v16, vcc, s50, v14
	v_lshl_add_u64 v[12:13], v[12:13], 0, v[2:3]
	s_nop 0
	v_addc_co_u32_e32 v17, vcc, 0, v15, vcc
	global_load_dwordx4 v[60:63], v[12:13], off
	s_nop 0
	global_load_dwordx4 v[220:223], v[16:17], off
	v_add_u32_e32 v24, 32, v5
	v_add_u32_e32 v14, 0xffffc000, v24
	v_lshrrev_b32_e32 v13, 3, v14
	v_ashrrev_i32_e32 v12, 11, v24
	v_ashrrev_i32_e32 v25, 31, v24
	v_add_u32_e32 v13, 8, v13
	v_cmp_gt_i32_e32 vcc, s3, v24
	s_nop 1
	v_cndmask_b32_e32 v16, v13, v12, vcc
	v_cndmask_b32_e32 v13, 0, v25, vcc
	v_cndmask_b32_e32 v12, v14, v24, vcc
	v_cndmask_b32_e32 v15, v36, v37, vcc
	v_cndmask_b32_e32 v14, v38, v39, vcc
	v_lshlrev_b64 v[12:13], 12, v[12:13]
	v_mad_i64_i32 v[16:17], s[24:25], v16, s48, v[26:27]
	v_lshl_add_u64 v[12:13], v[14:15], 0, v[12:13]
	v_lshl_add_u64 v[14:15], v[16:17], 0, v[2:3]
	v_add_co_u32_e32 v16, vcc, s50, v14
	v_lshl_add_u64 v[12:13], v[12:13], 0, v[2:3]
	s_nop 0
	v_addc_co_u32_e32 v17, vcc, 0, v15, vcc
	global_load_dwordx4 v[126:129], v[12:13], off
	s_nop 0
	global_load_dwordx4 v[224:227], v[16:17], off
	v_add_u32_e32 v24, 32, v4
	v_add_u32_e32 v14, 0xffffc000, v24
	v_lshrrev_b32_e32 v13, 3, v14
	v_ashrrev_i32_e32 v12, 11, v24
	v_ashrrev_i32_e32 v25, 31, v24
	v_add_u32_e32 v13, 8, v13
	v_cmp_gt_i32_e32 vcc, s3, v24
	s_nop 1
	v_cndmask_b32_e32 v16, v13, v12, vcc
	v_cndmask_b32_e32 v13, 0, v25, vcc
	v_cndmask_b32_e32 v12, v14, v24, vcc
	v_cndmask_b32_e32 v15, v36, v37, vcc
	v_cndmask_b32_e32 v14, v38, v39, vcc
	v_lshlrev_b64 v[12:13], 12, v[12:13]
	v_mad_i64_i32 v[16:17], s[24:25], v16, s48, v[26:27]
	v_lshl_add_u64 v[12:13], v[14:15], 0, v[12:13]
	v_lshl_add_u64 v[14:15], v[16:17], 0, v[2:3]
	v_add_co_u32_e32 v16, vcc, s50, v14
	v_lshl_add_u64 v[12:13], v[12:13], 0, v[2:3]
	s_nop 0
	v_addc_co_u32_e32 v17, vcc, 0, v15, vcc
	global_load_dwordx4 v[130:133], v[12:13], off
	s_nop 0
	global_load_dwordx4 v[228:231], v[16:17], off
	v_add_u32_e32 v24, 64, v7
	v_add_u32_e32 v14, 0xffffc000, v24
	v_lshrrev_b32_e32 v13, 3, v14
	v_ashrrev_i32_e32 v12, 11, v24
	v_ashrrev_i32_e32 v25, 31, v24
	v_add_u32_e32 v13, 8, v13
	v_cmp_gt_i32_e32 vcc, s3, v24
	s_nop 1
	v_cndmask_b32_e32 v16, v13, v12, vcc
	v_cndmask_b32_e32 v13, 0, v25, vcc
	v_cndmask_b32_e32 v12, v14, v24, vcc
	v_cndmask_b32_e32 v15, v36, v37, vcc
	v_cndmask_b32_e32 v14, v38, v39, vcc
	v_lshlrev_b64 v[12:13], 12, v[12:13]
	v_mad_i64_i32 v[16:17], s[24:25], v16, s48, v[26:27]
	v_lshl_add_u64 v[12:13], v[14:15], 0, v[12:13]
	v_lshl_add_u64 v[14:15], v[16:17], 0, v[2:3]
	v_add_co_u32_e32 v16, vcc, s50, v14
	v_lshl_add_u64 v[12:13], v[12:13], 0, v[2:3]
	s_nop 0
	v_addc_co_u32_e32 v17, vcc, 0, v15, vcc
	global_load_dwordx4 v[134:137], v[12:13], off
	s_nop 0
	global_load_dwordx4 v[232:235], v[16:17], off
	v_add_u32_e32 v24, 64, v6
	v_add_u32_e32 v14, 0xffffc000, v24
	v_lshrrev_b32_e32 v13, 3, v14
	v_ashrrev_i32_e32 v12, 11, v24
	v_ashrrev_i32_e32 v25, 31, v24
	v_add_u32_e32 v13, 8, v13
	v_cmp_gt_i32_e32 vcc, s3, v24
	s_nop 1
	v_cndmask_b32_e32 v16, v13, v12, vcc
	v_cndmask_b32_e32 v13, 0, v25, vcc
	v_cndmask_b32_e32 v12, v14, v24, vcc
	v_cndmask_b32_e32 v15, v36, v37, vcc
	v_cndmask_b32_e32 v14, v38, v39, vcc
	v_lshlrev_b64 v[12:13], 12, v[12:13]
	v_mad_i64_i32 v[16:17], s[24:25], v16, s48, v[26:27]
	v_lshl_add_u64 v[12:13], v[14:15], 0, v[12:13]
	v_lshl_add_u64 v[14:15], v[16:17], 0, v[2:3]
	v_add_co_u32_e32 v16, vcc, s50, v14
	v_lshl_add_u64 v[12:13], v[12:13], 0, v[2:3]
	s_nop 0
	v_addc_co_u32_e32 v17, vcc, 0, v15, vcc
	global_load_dwordx4 v[138:141], v[12:13], off
	s_nop 0
	global_load_dwordx4 v[240:243], v[16:17], off
	v_add_u32_e32 v24, 64, v5
	v_add_u32_e32 v14, 0xffffc000, v24
	v_lshrrev_b32_e32 v13, 3, v14
	v_ashrrev_i32_e32 v12, 11, v24
	v_ashrrev_i32_e32 v25, 31, v24
	v_add_u32_e32 v13, 8, v13
	v_cmp_gt_i32_e32 vcc, s3, v24
	s_nop 1
	v_cndmask_b32_e32 v16, v13, v12, vcc
	v_cndmask_b32_e32 v13, 0, v25, vcc
	v_cndmask_b32_e32 v12, v14, v24, vcc
	v_cndmask_b32_e32 v15, v36, v37, vcc
	v_cndmask_b32_e32 v14, v38, v39, vcc
	v_lshlrev_b64 v[12:13], 12, v[12:13]
	v_mad_i64_i32 v[16:17], s[24:25], v16, s48, v[26:27]
	v_lshl_add_u64 v[12:13], v[14:15], 0, v[12:13]
	v_lshl_add_u64 v[14:15], v[16:17], 0, v[2:3]
	v_add_co_u32_e32 v16, vcc, s50, v14
	v_lshl_add_u64 v[12:13], v[12:13], 0, v[2:3]
	s_nop 0
	v_addc_co_u32_e32 v17, vcc, 0, v15, vcc
	global_load_dwordx4 v[142:145], v[12:13], off
	s_nop 0
	global_load_dwordx4 v[244:247], v[16:17], off
	v_add_u32_e32 v24, 64, v4
	v_add_u32_e32 v14, 0xffffc000, v24
	v_lshrrev_b32_e32 v13, 3, v14
	v_ashrrev_i32_e32 v12, 11, v24
	v_ashrrev_i32_e32 v25, 31, v24
	v_add_u32_e32 v13, 8, v13
	v_cmp_gt_i32_e32 vcc, s3, v24
	s_nop 1
	v_cndmask_b32_e32 v16, v13, v12, vcc
	v_cndmask_b32_e32 v13, 0, v25, vcc
	v_cndmask_b32_e32 v12, v14, v24, vcc
	v_cndmask_b32_e32 v15, v36, v37, vcc
	v_cndmask_b32_e32 v14, v38, v39, vcc
	v_lshlrev_b64 v[12:13], 12, v[12:13]
	v_mad_i64_i32 v[16:17], s[24:25], v16, s48, v[26:27]
	v_lshl_add_u64 v[12:13], v[14:15], 0, v[12:13]
	v_lshl_add_u64 v[14:15], v[16:17], 0, v[2:3]
	v_add_co_u32_e32 v16, vcc, s50, v14
	v_lshl_add_u64 v[12:13], v[12:13], 0, v[2:3]
	s_nop 0
	v_addc_co_u32_e32 v17, vcc, 0, v15, vcc
	global_load_dwordx4 v[154:157], v[12:13], off
	s_nop 0
	global_load_dwordx4 v[248:251], v[16:17], off
	v_add_u32_e32 v24, 0x60, v7
	v_add_u32_e32 v14, 0xffffc000, v24
	v_lshrrev_b32_e32 v13, 3, v14
	v_ashrrev_i32_e32 v12, 11, v24
	v_ashrrev_i32_e32 v25, 31, v24
	v_add_u32_e32 v13, 8, v13
	v_cmp_gt_i32_e32 vcc, s3, v24
	s_nop 1
	v_cndmask_b32_e32 v16, v13, v12, vcc
	v_cndmask_b32_e32 v13, 0, v25, vcc
	v_cndmask_b32_e32 v12, v14, v24, vcc
	v_cndmask_b32_e32 v15, v36, v37, vcc
	v_cndmask_b32_e32 v14, v38, v39, vcc
	v_lshlrev_b64 v[12:13], 12, v[12:13]
	v_mad_i64_i32 v[16:17], s[24:25], v16, s48, v[26:27]
	v_lshl_add_u64 v[12:13], v[14:15], 0, v[12:13]
	v_lshl_add_u64 v[14:15], v[16:17], 0, v[2:3]
	v_add_co_u32_e32 v16, vcc, s50, v14
	v_lshl_add_u64 v[12:13], v[12:13], 0, v[2:3]
	s_nop 0
	v_addc_co_u32_e32 v17, vcc, 0, v15, vcc
	global_load_dwordx4 v[158:161], v[12:13], off
	s_nop 0
	global_load_dwordx4 v[252:255], v[16:17], off
	v_add_u32_e32 v24, 0x60, v6
	v_add_u32_e32 v14, 0xffffc000, v24
	v_lshrrev_b32_e32 v13, 3, v14
	v_ashrrev_i32_e32 v12, 11, v24
	v_ashrrev_i32_e32 v25, 31, v24
	v_add_u32_e32 v13, 8, v13
	v_cmp_gt_i32_e32 vcc, s3, v24
	s_nop 1
	v_cndmask_b32_e32 v16, v13, v12, vcc
	v_cndmask_b32_e32 v13, 0, v25, vcc
	v_cndmask_b32_e32 v12, v14, v24, vcc
	v_cndmask_b32_e32 v15, v36, v37, vcc
	v_cndmask_b32_e32 v14, v38, v39, vcc
	v_lshlrev_b64 v[12:13], 12, v[12:13]
	v_mad_i64_i32 v[16:17], s[24:25], v16, s48, v[26:27]
	v_lshl_add_u64 v[12:13], v[14:15], 0, v[12:13]
	v_lshl_add_u64 v[14:15], v[16:17], 0, v[2:3]
	v_add_co_u32_e32 v16, vcc, s50, v14
	v_lshl_add_u64 v[12:13], v[12:13], 0, v[2:3]
	s_nop 0
	v_addc_co_u32_e32 v17, vcc, 0, v15, vcc
	global_load_dwordx4 v[162:165], v[12:13], off
	s_nop 0
	global_load_dwordx4 v[112:115], v[16:17], off
	v_add_u32_e32 v24, 0x60, v5
	v_add_u32_e32 v14, 0xffffc000, v24
	v_lshrrev_b32_e32 v13, 3, v14
	v_ashrrev_i32_e32 v12, 11, v24
	v_ashrrev_i32_e32 v25, 31, v24
	v_add_u32_e32 v13, 8, v13
	v_cmp_gt_i32_e32 vcc, s3, v24
	s_nop 1
	v_cndmask_b32_e32 v16, v13, v12, vcc
	v_cndmask_b32_e32 v13, 0, v25, vcc
	v_cndmask_b32_e32 v12, v14, v24, vcc
	v_cndmask_b32_e32 v15, v36, v37, vcc
	v_cndmask_b32_e32 v14, v38, v39, vcc
	v_lshlrev_b64 v[12:13], 12, v[12:13]
	v_mad_i64_i32 v[16:17], s[24:25], v16, s48, v[26:27]
	v_lshl_add_u64 v[12:13], v[14:15], 0, v[12:13]
	v_lshl_add_u64 v[14:15], v[16:17], 0, v[2:3]
	v_add_co_u32_e32 v16, vcc, s50, v14
	v_lshl_add_u64 v[12:13], v[12:13], 0, v[2:3]
	s_nop 0
	v_addc_co_u32_e32 v17, vcc, 0, v15, vcc
	global_load_dwordx4 v[166:169], v[12:13], off
	s_nop 0
	global_load_dwordx4 v[118:121], v[16:17], off
	v_add_u32_e32 v24, 0x60, v4
	v_add_u32_e32 v14, 0xffffc000, v24
	v_lshrrev_b32_e32 v13, 3, v14
	v_ashrrev_i32_e32 v12, 11, v24
	v_ashrrev_i32_e32 v25, 31, v24
	v_add_u32_e32 v13, 8, v13
	v_cmp_gt_i32_e32 vcc, s3, v24
	s_nop 1
	v_cndmask_b32_e32 v16, v13, v12, vcc
	v_cndmask_b32_e32 v13, 0, v25, vcc
	v_cndmask_b32_e32 v12, v14, v24, vcc
	v_cndmask_b32_e32 v15, v36, v37, vcc
	v_cndmask_b32_e32 v14, v38, v39, vcc
	v_lshlrev_b64 v[12:13], 12, v[12:13]
	v_mad_i64_i32 v[16:17], s[24:25], v16, s48, v[26:27]
	v_lshl_add_u64 v[12:13], v[14:15], 0, v[12:13]
	v_lshl_add_u64 v[14:15], v[16:17], 0, v[2:3]
	v_add_co_u32_e32 v16, vcc, s50, v14
	v_lshl_add_u64 v[12:13], v[12:13], 0, v[2:3]
	s_nop 0
	v_addc_co_u32_e32 v17, vcc, 0, v15, vcc
	global_load_dwordx4 v[170:173], v[12:13], off
	s_nop 0
	global_load_dwordx4 v[70:73], v[16:17], off
	ds_read_b128 v[20:23], v8
	ds_read_b128 v[28:31], v9
	s_waitcnt vmcnt(30) lgkmcnt(1)
	v_pk_fma_f32 v[40:41], v[20:21], v[174:175], v[40:41]
	v_pk_fma_f32 v[42:43], v[22:23], v[176:177], v[42:43]
	v_add_u32_e32 v24, 0, v7
	v_ashrrev_i32_e32 v25, 31, v24
	v_lshlrev_b64 v[24:25], 12, v[24:25]
	v_lshl_add_u64 v[24:25], v[0:1], 0, v[24:25]
	global_store_dwordx4 v[24:25], v[40:43], off
	ds_read_b128 v[20:23], v10
	s_waitcnt vmcnt(29) lgkmcnt(1)
	v_pk_fma_f32 v[44:45], v[28:29], v[178:179], v[44:45]
	v_pk_fma_f32 v[46:47], v[30:31], v[180:181], v[46:47]
	v_add_u32_e32 v24, 0, v6
	v_ashrrev_i32_e32 v25, 31, v24
	v_lshlrev_b64 v[24:25], 12, v[24:25]
	v_lshl_add_u64 v[24:25], v[0:1], 0, v[24:25]
	global_store_dwordx4 v[24:25], v[44:47], off
	ds_read_b128 v[28:31], v11
	s_waitcnt vmcnt(28) lgkmcnt(1)
	v_pk_fma_f32 v[48:49], v[20:21], v[182:183], v[48:49]
	v_pk_fma_f32 v[50:51], v[22:23], v[184:185], v[50:51]
	v_add_u32_e32 v24, 0, v5
	v_ashrrev_i32_e32 v25, 31, v24
	v_lshlrev_b64 v[24:25], 12, v[24:25]
	v_lshl_add_u64 v[24:25], v[0:1], 0, v[24:25]
	global_store_dwordx4 v[24:25], v[48:51], off
	ds_read_b128 v[20:23], v8 offset:16896
	s_waitcnt vmcnt(27) lgkmcnt(1)
	v_pk_fma_f32 v[52:53], v[28:29], v[186:187], v[52:53]
	v_pk_fma_f32 v[54:55], v[30:31], v[188:189], v[54:55]
	v_add_u32_e32 v24, 0, v4
	v_ashrrev_i32_e32 v25, 31, v24
	v_lshlrev_b64 v[24:25], 12, v[24:25]
	v_lshl_add_u64 v[24:25], v[0:1], 0, v[24:25]
	global_store_dwordx4 v[24:25], v[52:55], off
	ds_read_b128 v[28:31], v9 offset:16896
	s_waitcnt vmcnt(26) lgkmcnt(1)
	v_pk_fma_f32 v[56:57], v[20:21], v[190:191], v[56:57]
	v_pk_fma_f32 v[58:59], v[22:23], v[192:193], v[58:59]
	v_add_u32_e32 v24, 32, v7
	v_ashrrev_i32_e32 v25, 31, v24
	v_lshlrev_b64 v[24:25], 12, v[24:25]
	v_lshl_add_u64 v[24:25], v[0:1], 0, v[24:25]
	global_store_dwordx4 v[24:25], v[56:59], off
	ds_read_b128 v[20:23], v10 offset:16896
	s_waitcnt vmcnt(25) lgkmcnt(1)
	v_pk_fma_f32 v[60:61], v[28:29], v[220:221], v[60:61]
	v_pk_fma_f32 v[62:63], v[30:31], v[222:223], v[62:63]
	v_add_u32_e32 v24, 32, v6
	v_ashrrev_i32_e32 v25, 31, v24
	v_lshlrev_b64 v[24:25], 12, v[24:25]
	v_lshl_add_u64 v[24:25], v[0:1], 0, v[24:25]
	global_store_dwordx4 v[24:25], v[60:63], off
	ds_read_b128 v[28:31], v11 offset:16896
	s_waitcnt vmcnt(24) lgkmcnt(1)
	v_pk_fma_f32 v[126:127], v[20:21], v[224:225], v[126:127]
	v_pk_fma_f32 v[128:129], v[22:23], v[226:227], v[128:129]
	v_add_u32_e32 v24, 32, v5
	v_ashrrev_i32_e32 v25, 31, v24
	v_lshlrev_b64 v[24:25], 12, v[24:25]
	v_lshl_add_u64 v[24:25], v[0:1], 0, v[24:25]
	global_store_dwordx4 v[24:25], v[126:129], off
	ds_read_b128 v[20:23], v8 offset:33792
	s_waitcnt vmcnt(23) lgkmcnt(1)
	v_pk_fma_f32 v[130:131], v[28:29], v[228:229], v[130:131]
	v_pk_fma_f32 v[132:133], v[30:31], v[230:231], v[132:133]
	v_add_u32_e32 v24, 32, v4
	v_ashrrev_i32_e32 v25, 31, v24
	v_lshlrev_b64 v[24:25], 12, v[24:25]
	v_lshl_add_u64 v[24:25], v[0:1], 0, v[24:25]
	global_store_dwordx4 v[24:25], v[130:133], off
	ds_read_b128 v[28:31], v9 offset:33792
	s_waitcnt vmcnt(22) lgkmcnt(1)
	v_pk_fma_f32 v[134:135], v[20:21], v[232:233], v[134:135]
	v_pk_fma_f32 v[136:137], v[22:23], v[234:235], v[136:137]
	v_add_u32_e32 v24, 64, v7
	v_ashrrev_i32_e32 v25, 31, v24
	v_lshlrev_b64 v[24:25], 12, v[24:25]
	v_lshl_add_u64 v[24:25], v[0:1], 0, v[24:25]
	global_store_dwordx4 v[24:25], v[134:137], off
	ds_read_b128 v[20:23], v10 offset:33792
	s_waitcnt vmcnt(21) lgkmcnt(1)
	v_pk_fma_f32 v[138:139], v[28:29], v[240:241], v[138:139]
	v_pk_fma_f32 v[140:141], v[30:31], v[242:243], v[140:141]
	v_add_u32_e32 v24, 64, v6
	v_ashrrev_i32_e32 v25, 31, v24
	v_lshlrev_b64 v[24:25], 12, v[24:25]
	v_lshl_add_u64 v[24:25], v[0:1], 0, v[24:25]
	global_store_dwordx4 v[24:25], v[138:141], off
	ds_read_b128 v[28:31], v11 offset:33792
	s_waitcnt vmcnt(20) lgkmcnt(1)
	v_pk_fma_f32 v[142:143], v[20:21], v[244:245], v[142:143]
	v_pk_fma_f32 v[144:145], v[22:23], v[246:247], v[144:145]
	v_add_u32_e32 v24, 64, v5
	v_ashrrev_i32_e32 v25, 31, v24
	v_lshlrev_b64 v[24:25], 12, v[24:25]
	v_lshl_add_u64 v[24:25], v[0:1], 0, v[24:25]
	global_store_dwordx4 v[24:25], v[142:145], off
	ds_read_b128 v[20:23], v8 offset:50688
	s_waitcnt vmcnt(19) lgkmcnt(1)
	v_pk_fma_f32 v[154:155], v[28:29], v[248:249], v[154:155]
	v_pk_fma_f32 v[156:157], v[30:31], v[250:251], v[156:157]
	v_add_u32_e32 v24, 64, v4
	v_ashrrev_i32_e32 v25, 31, v24
	v_lshlrev_b64 v[24:25], 12, v[24:25]
	v_lshl_add_u64 v[24:25], v[0:1], 0, v[24:25]
	global_store_dwordx4 v[24:25], v[154:157], off
	ds_read_b128 v[28:31], v9 offset:50688
	s_waitcnt vmcnt(18) lgkmcnt(1)
	v_pk_fma_f32 v[158:159], v[20:21], v[252:253], v[158:159]
	v_pk_fma_f32 v[160:161], v[22:23], v[254:255], v[160:161]
	v_add_u32_e32 v24, 0x60, v7
	v_ashrrev_i32_e32 v25, 31, v24
	v_lshlrev_b64 v[24:25], 12, v[24:25]
	v_lshl_add_u64 v[24:25], v[0:1], 0, v[24:25]
	global_store_dwordx4 v[24:25], v[158:161], off
	ds_read_b128 v[20:23], v10 offset:50688
	s_waitcnt vmcnt(17) lgkmcnt(1)
	v_pk_fma_f32 v[162:163], v[28:29], v[112:113], v[162:163]
	v_pk_fma_f32 v[164:165], v[30:31], v[114:115], v[164:165]
	v_add_u32_e32 v24, 0x60, v6
	v_ashrrev_i32_e32 v25, 31, v24
	v_lshlrev_b64 v[24:25], 12, v[24:25]
	v_lshl_add_u64 v[24:25], v[0:1], 0, v[24:25]
	global_store_dwordx4 v[24:25], v[162:165], off
	ds_read_b128 v[28:31], v11 offset:50688
	s_waitcnt vmcnt(16) lgkmcnt(1)
	v_pk_fma_f32 v[166:167], v[20:21], v[118:119], v[166:167]
	v_pk_fma_f32 v[168:169], v[22:23], v[120:121], v[168:169]
	v_add_u32_e32 v24, 0x60, v5
	v_ashrrev_i32_e32 v25, 31, v24
	v_lshlrev_b64 v[24:25], 12, v[24:25]
	v_lshl_add_u64 v[24:25], v[0:1], 0, v[24:25]
	global_store_dwordx4 v[24:25], v[166:169], off
	s_waitcnt vmcnt(15) lgkmcnt(0)
	v_pk_fma_f32 v[170:171], v[28:29], v[70:71], v[170:171]
	v_pk_fma_f32 v[172:173], v[30:31], v[72:73], v[172:173]
	v_add_u32_e32 v24, 0x60, v4
	v_ashrrev_i32_e32 v25, 31, v24
	v_lshlrev_b64 v[24:25], 12, v[24:25]
	v_lshl_add_u64 v[24:25], v[0:1], 0, v[24:25]
	global_store_dwordx4 v[24:25], v[170:173], off
	s_movk_i32 s14, 0x80
	s_barrier
	s_branch .LBB0_724
